# attn_b: K/V global prefetch two tiles ahead (second staging set in registers borrowed from hoisted constants)
# speedup vs baseline: 1.0043x; 1.0043x over previous
.LBB0_641:
	s_ashr_i32 s0, s5, 7
	s_mul_i32 s23, s0, 0x3e00000
	s_mul_hi_i32 s17, s0, 0x3e00000
	s_add_u32 s0, s2, s23
	s_addc_u32 s1, s4, s17
	s_lshl_b32 s8, s5, 8
	s_and_b32 s8, s8, 0xf00
	v_and_b32_e32 v32, 15, v2
	v_lshl_add_u32 v0, v0, 5, s8
	s_waitcnt lgkmcnt(0)
	v_or_b32_e32 v3, v0, v32
	v_mov_b64_e32 v[4:5], s[0:1]
	v_mad_i64_i32 v[6:7], s[0:1], v3, s65, v[4:5]
	s_lshl_b32 s0, s5, 3
	v_or_b32_e32 v3, 16, v3
	s_and_b32 s8, s0, 0x380
	v_mad_i64_i32 v[8:9], s[0:1], v3, s65, v[4:5]
	v_ashrrev_i32_e32 v3, 3, v2
	s_waitcnt lgkmcnt(0)
	v_bfe_u32 v33, v2, 4, 2
	v_lshl_add_u64 v[6:7], v[6:7], 0, s[8:9]
	s_mov_b64 s[12:13], 0x1000
	v_lshl_add_u64 v[8:9], v[8:9], 0, s[8:9]
	v_mad_i64_i32 v[4:5], s[0:1], v3, s65, v[4:5]
	v_lshl_add_u64 v[110:111], v[6:7], 0, s[12:13]
	v_lshlrev_b32_e32 v0, 4, v33
	v_lshl_add_u64 v[108:109], v[8:9], 0, s[12:13]
	s_and_b32 s0, s5, 64
	v_lshl_add_u64 v[6:7], v[110:111], 0, v[0:1]
	v_lshl_add_u64 v[28:29], v[108:109], 0, v[0:1]
	s_lshl_b32 s8, s0, 1
	v_lshlrev_b32_e32 v0, 4, v2
	v_and_b32_e32 v0, 0x70, v0
	v_lshl_add_u64 v[4:5], v[4:5], 0, s[8:9]
	v_lshl_add_u64 v[30:31], v[4:5], 0, v[0:1]
	v_add_co_u32_e32 v4, vcc, s71, v30
	v_lshlrev_b32_e32 v118, 2, v33
	s_nop 0
	v_addc_co_u32_e32 v5, vcc, 0, v31, vcc
	global_load_dwordx4 v[20:23], v[4:5], off offset:1024
	global_load_dwordx4 v[24:27], v[4:5], off offset:1280
	global_load_dwordx4 v[16:19], v[6:7], off
	global_load_dwordx4 v[8:11], v[6:7], off offset:64
	global_load_dwordx4 v[12:15], v[28:29], off
	s_nop 0
	global_load_dwordx4 v[4:7], v[28:29], off offset:64
	v_bfe_u32 v29, v2, 2, 2
	v_lshlrev_b32_e32 v28, 3, v2
	v_or_b32_e32 v29, v118, v29
	s_mov_b64 s[18:19], 0x1400
	v_lshlrev_b32_e32 v34, 3, v33
	v_mul_lo_u32 v35, v3, s40
	v_mul_u32_u24_e32 v32, 0x50, v32
	v_and_b32_e32 v28, 24, v28
	v_mul_u32_u24_e32 v29, 0xa0, v29
	v_lshl_add_u64 v[112:113], v[30:31], 0, s[18:19]
	s_mov_b64 s[18:19], 0x1500
	s_mov_b64 s[88:89], 0x1000
	s_mov_b64 s[0:1], -1
	v_lshlrev_b32_e32 v116, 1, v32
	v_add3_u32 v119, 0, v29, v28
	s_cmp_lt_i32 s30, 4
	v_add3_u32 v120, 0, v35, v0
	v_lshl_add_u64 v[114:115], v[30:31], 0, s[18:19]
	v_lshlrev_b32_e32 v0, 1, v34
	s_barrier
	s_waitcnt vmcnt(5)
	ds_write_b128 v120, v[20:23]
	s_waitcnt vmcnt(4)
	ds_write_b128 v120, v[24:27] offset:20480
	s_waitcnt lgkmcnt(0)
	s_barrier
	s_cbranch_scc1 .Lb_groupA
	s_waitcnt vmcnt(0)
	v_mov_b32_e32 v34, 0
	v_mov_b32_e32 v35, 0
	v_mov_b32_e32 v36, 0
	v_mov_b32_e32 v37, 0
	v_mov_b32_e32 v42, 0
	v_mov_b32_e32 v43, 0
	v_mov_b32_e32 v44, 0
	v_mov_b32_e32 v45, 0
	v_mov_b32_e32 v56, 0
	v_mov_b32_e32 v57, 0
	v_mov_b32_e32 v58, 0
	v_mov_b32_e32 v59, 0
	v_mov_b32_e32 v60, 0
	v_mov_b32_e32 v61, 0
	v_mov_b32_e32 v62, 0
	v_mov_b32_e32 v63, 0
	v_mov_b32_e32 v20, 0
	v_mov_b32_e32 v21, 0
	v_mov_b32_e32 v22, 0
	v_mov_b32_e32 v23, 0
	v_mov_b32_e32 v24, 0
	v_mov_b32_e32 v25, 0
	v_mov_b32_e32 v26, 0
	v_mov_b32_e32 v27, 0
	v_mov_b32_e32 v38, 0
	v_mov_b32_e32 v39, 0
	v_mov_b32_e32 v40, 0
	v_mov_b32_e32 v41, 0
	v_mov_b32_e32 v28, 0
	v_mov_b32_e32 v29, 0
	v_mov_b32_e32 v30, 0
	v_mov_b32_e32 v31, 0
	v_mov_b32_e32 v180, 0
	v_mov_b32_e32 v181, 0
	v_mov_b32_e32 v182, 0
	v_mov_b32_e32 v183, 0
	v_mov_b32_e32 v184, 0
	v_mov_b32_e32 v185, 0
	v_mov_b32_e32 v186, 0
	v_mov_b32_e32 v187, 0
	v_mov_b32_e32 v188, 0
	v_mov_b32_e32 v189, 0
	v_mov_b32_e32 v190, 0
	v_mov_b32_e32 v191, 0
	v_mov_b32_e32 v204, 0
	v_mov_b32_e32 v205, 0
	v_mov_b32_e32 v206, 0
	v_mov_b32_e32 v207, 0
	v_mov_b32_e32 v48, 0
	v_mov_b32_e32 v49, 0
	v_mov_b32_e32 v50, 0
	v_mov_b32_e32 v51, 0
	v_mov_b32_e32 v52, 0
	v_mov_b32_e32 v53, 0
	v_mov_b32_e32 v54, 0
	v_mov_b32_e32 v55, 0
	v_mov_b32_e32 v80, 0
	v_mov_b32_e32 v64, 0
	v_add_u32_e32 v75, v116, v0
	v_readfirstlane_b32 s80, v112
	v_readfirstlane_b32 s81, v113
	v_readfirstlane_b32 s86, v114
	v_readfirstlane_b32 s87, v115
	s_nop 3
	v_subrev_u32_e32 v71, s80, v112
	v_subrev_u32_e32 v73, s86, v114
	s_mov_b32 s20, 0
	s_mov_b32 s42, 0
	s_mov_b32 s43, 0
	s_mov_b32 s51, 10240
	s_mov_b32 s30, 0xf8000
	s_mov_b32 s66, 0xff800000
	s_mov_b32 s67, 0xff800000
	v_add_u32_e32 v72, s42, v119
	v_add_u32_e32 v74, s51, v120
	s_add_u32 s96, s80, s30
	s_addc_u32 s97, s81, 0
	s_add_u32 s98, s86, s30
	s_addc_u32 s99, s87, 0
	global_load_dwordx4 v[138:141], v71, s[96:97]
	global_load_dwordx4 v[142:145], v73, s[98:99]
	s_mov_b32 s30, 0x1f0000
	v_add_u32_e32 v72, s42, v119
	v_add_u32_e32 v74, s51, v120
	s_add_u32 s96, s80, s30
	s_addc_u32 s97, s81, 0
	s_add_u32 s98, s86, s30
	s_addc_u32 s99, s87, 0
	v_mov_b32_e32 v88, 0xff800000
	v_mov_b32_e32 v89, 0xff800000
	v_mov_b32_e32 v90, 0xff800000
	v_mov_b32_e32 v91, 0xff800000
	v_mov_b32_e32 v92, 0xff800000
	v_mov_b32_e32 v93, 0xff800000
	v_mov_b32_e32 v94, 0xff800000
	v_mov_b32_e32 v95, 0xff800000
	v_mov_b32_e32 v96, 0xff800000
	v_mov_b32_e32 v97, 0xff800000
	v_mov_b32_e32 v98, 0xff800000
	v_mov_b32_e32 v99, 0xff800000
	v_mov_b32_e32 v100, 0xff800000
	v_mov_b32_e32 v101, 0xff800000
	v_mov_b32_e32 v102, 0xff800000
	v_mov_b32_e32 v103, 0xff800000
	v_mov_b32_e32 v104, 0xff800000
	v_mov_b32_e32 v105, 0xff800000
	v_mov_b32_e32 v106, 0xff800000
	v_mov_b32_e32 v107, 0xff800000
	v_mov_b32_e32 v168, 0xff800000
	v_mov_b32_e32 v169, 0xff800000
	v_mov_b32_e32 v170, 0xff800000
	v_mov_b32_e32 v171, 0xff800000
	v_mov_b32_e32 v172, 0xff800000
	v_mov_b32_e32 v173, 0xff800000
	v_mov_b32_e32 v174, 0xff800000
	v_mov_b32_e32 v175, 0xff800000
	v_mov_b32_e32 v176, 0xff800000
	v_mov_b32_e32 v177, 0xff800000
	v_mov_b32_e32 v178, 0xff800000
	v_mov_b32_e32 v179, 0xff800000

.Lb_back_B0_1:
	v_add_f32_e32 v64, v64, v67
	v_cvt_pk_bf16_f32 v184, v236, v237
	v_cvt_pk_bf16_f32 v185, v238, v239
	v_cvt_pk_bf16_f32 v186, v240, v241
	v_cvt_pk_bf16_f32 v187, v242, v243
	v_cvt_pk_bf16_f32 v204, v244, v245
	v_cvt_pk_bf16_f32 v205, v246, v247
	v_cvt_pk_bf16_f32 v206, v248, v249
	v_cvt_pk_bf16_f32 v207, v250, v251
	ds_read_b128 v[232:235], v75 offset:5120
	s_waitcnt lgkmcnt(4)
	v_mfma_f32_16x16x32_bf16 v[88:91], v[216:219], v[16:19], v[48:51]
	v_mfma_f32_16x16x32_bf16 v[104:107], v[216:219], v[12:15], v[52:55]
	ds_read_b128 v[216:219], v75 offset:5184
	s_waitcnt lgkmcnt(4)
	v_mfma_f32_16x16x32_bf16 v[88:91], v[220:223], v[8:11], v[88:91]
	v_mfma_f32_16x16x32_bf16 v[104:107], v[220:223], v[4:7], v[104:107]
	ds_read_b128 v[220:223], v75 offset:7680
	s_waitcnt lgkmcnt(4)
	v_mfma_f32_16x16x32_bf16 v[92:95], v[224:227], v[16:19], v[48:51]
	v_mfma_f32_16x16x32_bf16 v[168:171], v[224:227], v[12:15], v[52:55]
	ds_read_b128 v[224:227], v75 offset:7744
	s_waitcnt lgkmcnt(4)
	v_mfma_f32_16x16x32_bf16 v[92:95], v[228:231], v[8:11], v[92:95]
	v_mfma_f32_16x16x32_bf16 v[168:171], v[228:231], v[4:7], v[168:171]
	ds_read_b64_tr_b16 v[228:229], v72 offset:20480
	ds_read_b64_tr_b16 v[230:231], v72 offset:23040
	s_waitcnt lgkmcnt(5)
	v_mfma_f32_16x16x32_bf16 v[96:99], v[232:235], v[16:19], v[48:51]
	v_mfma_f32_16x16x32_bf16 v[172:175], v[232:235], v[12:15], v[52:55]
	ds_read_b64_tr_b16 v[232:233], v72 offset:20512
	ds_read_b64_tr_b16 v[234:235], v72 offset:23072
	s_waitcnt lgkmcnt(6)
	v_mfma_f32_16x16x32_bf16 v[96:99], v[216:219], v[8:11], v[96:99]
	v_mfma_f32_16x16x32_bf16 v[172:175], v[216:219], v[4:7], v[172:175]
	ds_read_b64_tr_b16 v[216:217], v72 offset:20544
	ds_read_b64_tr_b16 v[218:219], v72 offset:23104
	s_waitcnt lgkmcnt(7)
	v_mfma_f32_16x16x32_bf16 v[100:103], v[220:223], v[16:19], v[48:51]
	v_mfma_f32_16x16x32_bf16 v[176:179], v[220:223], v[12:15], v[52:55]
	ds_read_b64_tr_b16 v[220:221], v72 offset:20576
	ds_read_b64_tr_b16 v[222:223], v72 offset:23136
	s_waitcnt lgkmcnt(8)
	v_mfma_f32_16x16x32_bf16 v[100:103], v[224:227], v[8:11], v[100:103]
	v_mfma_f32_16x16x32_bf16 v[176:179], v[224:227], v[4:7], v[176:179]
	ds_read_b64_tr_b16 v[224:225], v72 offset:25600
	ds_read_b64_tr_b16 v[226:227], v72 offset:28160
	s_waitcnt lgkmcnt(8)
	v_mfma_f32_16x16x32_bf16 v[34:37], v[228:231], v[180:183], v[34:37]
	v_mfma_f32_16x16x32_bf16 v[20:23], v[228:231], v[184:187], v[20:23]
	ds_read_b64_tr_b16 v[228:229], v72 offset:25632
	ds_read_b64_tr_b16 v[230:231], v72 offset:28192
	s_waitcnt lgkmcnt(8)
	v_mfma_f32_16x16x32_bf16 v[42:45], v[232:235], v[180:183], v[42:45]
	v_mfma_f32_16x16x32_bf16 v[24:27], v[232:235], v[184:187], v[24:27]
	ds_read_b64_tr_b16 v[232:233], v72 offset:25664
	ds_read_b64_tr_b16 v[234:235], v72 offset:28224
	s_waitcnt lgkmcnt(8)
	v_mfma_f32_16x16x32_bf16 v[56:59], v[216:219], v[180:183], v[56:59]
	v_mfma_f32_16x16x32_bf16 v[38:41], v[216:219], v[184:187], v[38:41]
	ds_read_b64_tr_b16 v[216:217], v72 offset:25696
	ds_read_b64_tr_b16 v[218:219], v72 offset:28256
	s_waitcnt lgkmcnt(8)
	v_mfma_f32_16x16x32_bf16 v[60:63], v[220:223], v[180:183], v[60:63]
	v_mfma_f32_16x16x32_bf16 v[28:31], v[220:223], v[184:187], v[28:31]
	s_waitcnt lgkmcnt(6)
	v_mfma_f32_16x16x32_bf16 v[34:37], v[224:227], v[188:191], v[34:37]
	v_mfma_f32_16x16x32_bf16 v[20:23], v[224:227], v[204:207], v[20:23]
	s_waitcnt lgkmcnt(4)
	v_mfma_f32_16x16x32_bf16 v[42:45], v[228:231], v[188:191], v[42:45]
	v_mfma_f32_16x16x32_bf16 v[24:27], v[228:231], v[204:207], v[24:27]
	s_waitcnt lgkmcnt(2)
	v_mfma_f32_16x16x32_bf16 v[56:59], v[232:235], v[188:191], v[56:59]
	v_mfma_f32_16x16x32_bf16 v[38:41], v[232:235], v[204:207], v[38:41]
	s_waitcnt lgkmcnt(0)
	v_mfma_f32_16x16x32_bf16 v[60:63], v[216:219], v[188:191], v[60:63]
	v_mfma_f32_16x16x32_bf16 v[28:31], v[216:219], v[204:207], v[28:31]
	s_mov_b32 s42, s43
	s_mov_b32 s43, s51
	s_add_i32 s51, s51, 10240
	s_cmp_lg_u32 s51, 30720
	s_cselect_b32 s51, s51, 0
	s_min_u32 s8, s20, 60
	s_add_i32 s8, s8, 3
	s_mul_i32 s30, s8, 0xf8000
	s_nop 1
	s_waitcnt vmcnt(2)
	ds_write_b128 v120, v[138:141] offset:10240
	ds_write_b128 v74, v[142:145] offset:20480
	s_mov_b32 s66, 0xff800000
	s_mov_b32 s67, 0xff800000
	s_cmp_ge_u32 s20, 1
	s_cselect_b32 s66, 0x5f800000, s66
	s_cselect_b32 s67, 0x42000000, s67
	s_add_i32 s20, s20, 1
	v_add_u32_e32 v72, s42, v119
	v_add_u32_e32 v74, s51, v120
	s_add_u32 s96, s80, s30
	s_addc_u32 s97, s81, 0
	s_add_u32 s98, s86, s30
	s_addc_u32 s99, s87, 0
	s_waitcnt lgkmcnt(0)
	s_barrier
	global_load_dwordx4 v[138:141], v71, s[96:97]
	global_load_dwordx4 v[142:145], v73, s[98:99]
	ds_read_b128 v[216:219], v75 offset:10240
	ds_read_b128 v[220:223], v75 offset:10304
	ds_read_b128 v[224:227], v75 offset:12800
	ds_read_b128 v[228:231], v75 offset:12864
	v_exp_f32_e32 v236, v88
	v_exp_f32_e32 v237, v89
	v_exp_f32_e32 v238, v90
	v_exp_f32_e32 v239, v91
	v_exp_f32_e32 v240, v92
	v_exp_f32_e32 v241, v93
	v_exp_f32_e32 v242, v94
	v_exp_f32_e32 v243, v95
	v_exp_f32_e32 v244, v96
	v_exp_f32_e32 v245, v97
	v_exp_f32_e32 v246, v98
	v_exp_f32_e32 v247, v99
	v_exp_f32_e32 v248, v100
	v_exp_f32_e32 v249, v101
	v_exp_f32_e32 v250, v102
	v_exp_f32_e32 v251, v103
	s_nop 0
	v_add_f32_e32 v67, v236, v237
	v_add_f32_e32 v67, v67, v238
	v_add_f32_e32 v67, v67, v239
	v_add_f32_e32 v67, v67, v240
	v_add_f32_e32 v67, v67, v241
	v_add_f32_e32 v67, v67, v242
	v_add_f32_e32 v67, v67, v243
	v_add_f32_e32 v67, v67, v244
	v_add_f32_e32 v67, v67, v245
	v_add_f32_e32 v67, v67, v246
	v_add_f32_e32 v67, v67, v247
	v_add_f32_e32 v67, v67, v248
	v_add_f32_e32 v67, v67, v249
	v_add_f32_e32 v67, v67, v250
	v_add_f32_e32 v67, v67, v251
	v_cmp_lt_f32_e32 vcc, s66, v67
	s_cbranch_vccnz .Lb_rare_B1_0

.Lb_back_B1_1:
	v_add_f32_e32 v64, v64, v67
	v_cvt_pk_bf16_f32 v184, v236, v237
	v_cvt_pk_bf16_f32 v185, v238, v239
	v_cvt_pk_bf16_f32 v186, v240, v241
	v_cvt_pk_bf16_f32 v187, v242, v243
	v_cvt_pk_bf16_f32 v204, v244, v245
	v_cvt_pk_bf16_f32 v205, v246, v247
	v_cvt_pk_bf16_f32 v206, v248, v249
	v_cvt_pk_bf16_f32 v207, v250, v251
	ds_read_b128 v[232:235], v75 offset:15360
	s_waitcnt lgkmcnt(4)
	v_mfma_f32_16x16x32_bf16 v[88:91], v[216:219], v[16:19], v[48:51]
	v_mfma_f32_16x16x32_bf16 v[104:107], v[216:219], v[12:15], v[52:55]
	ds_read_b128 v[216:219], v75 offset:15424
	s_waitcnt lgkmcnt(4)
	v_mfma_f32_16x16x32_bf16 v[88:91], v[220:223], v[8:11], v[88:91]
	v_mfma_f32_16x16x32_bf16 v[104:107], v[220:223], v[4:7], v[104:107]
	ds_read_b128 v[220:223], v75 offset:17920
	s_waitcnt lgkmcnt(4)
	v_mfma_f32_16x16x32_bf16 v[92:95], v[224:227], v[16:19], v[48:51]
	v_mfma_f32_16x16x32_bf16 v[168:171], v[224:227], v[12:15], v[52:55]
	ds_read_b128 v[224:227], v75 offset:17984
	s_waitcnt lgkmcnt(4)
	v_mfma_f32_16x16x32_bf16 v[92:95], v[228:231], v[8:11], v[92:95]
	v_mfma_f32_16x16x32_bf16 v[168:171], v[228:231], v[4:7], v[168:171]
	ds_read_b64_tr_b16 v[228:229], v72 offset:20480
	ds_read_b64_tr_b16 v[230:231], v72 offset:23040
	s_waitcnt lgkmcnt(5)
	v_mfma_f32_16x16x32_bf16 v[96:99], v[232:235], v[16:19], v[48:51]
	v_mfma_f32_16x16x32_bf16 v[172:175], v[232:235], v[12:15], v[52:55]
	ds_read_b64_tr_b16 v[232:233], v72 offset:20512
	ds_read_b64_tr_b16 v[234:235], v72 offset:23072
	s_waitcnt lgkmcnt(6)
	v_mfma_f32_16x16x32_bf16 v[96:99], v[216:219], v[8:11], v[96:99]
	v_mfma_f32_16x16x32_bf16 v[172:175], v[216:219], v[4:7], v[172:175]
	ds_read_b64_tr_b16 v[216:217], v72 offset:20544
	ds_read_b64_tr_b16 v[218:219], v72 offset:23104
	s_waitcnt lgkmcnt(7)
	v_mfma_f32_16x16x32_bf16 v[100:103], v[220:223], v[16:19], v[48:51]
	v_mfma_f32_16x16x32_bf16 v[176:179], v[220:223], v[12:15], v[52:55]
	ds_read_b64_tr_b16 v[220:221], v72 offset:20576
	ds_read_b64_tr_b16 v[222:223], v72 offset:23136
	s_waitcnt lgkmcnt(8)
	v_mfma_f32_16x16x32_bf16 v[100:103], v[224:227], v[8:11], v[100:103]
	v_mfma_f32_16x16x32_bf16 v[176:179], v[224:227], v[4:7], v[176:179]
	ds_read_b64_tr_b16 v[224:225], v72 offset:25600
	ds_read_b64_tr_b16 v[226:227], v72 offset:28160
	s_waitcnt lgkmcnt(8)
	v_mfma_f32_16x16x32_bf16 v[34:37], v[228:231], v[180:183], v[34:37]
	v_mfma_f32_16x16x32_bf16 v[20:23], v[228:231], v[184:187], v[20:23]
	ds_read_b64_tr_b16 v[228:229], v72 offset:25632
	ds_read_b64_tr_b16 v[230:231], v72 offset:28192
	s_waitcnt lgkmcnt(8)
	v_mfma_f32_16x16x32_bf16 v[42:45], v[232:235], v[180:183], v[42:45]
	v_mfma_f32_16x16x32_bf16 v[24:27], v[232:235], v[184:187], v[24:27]
	ds_read_b64_tr_b16 v[232:233], v72 offset:25664
	ds_read_b64_tr_b16 v[234:235], v72 offset:28224
	s_waitcnt lgkmcnt(8)
	v_mfma_f32_16x16x32_bf16 v[56:59], v[216:219], v[180:183], v[56:59]
	v_mfma_f32_16x16x32_bf16 v[38:41], v[216:219], v[184:187], v[38:41]
	ds_read_b64_tr_b16 v[216:217], v72 offset:25696
	ds_read_b64_tr_b16 v[218:219], v72 offset:28256
	s_waitcnt lgkmcnt(8)
	v_mfma_f32_16x16x32_bf16 v[60:63], v[220:223], v[180:183], v[60:63]
	v_mfma_f32_16x16x32_bf16 v[28:31], v[220:223], v[184:187], v[28:31]
	s_waitcnt lgkmcnt(6)
	v_mfma_f32_16x16x32_bf16 v[34:37], v[224:227], v[188:191], v[34:37]
	v_mfma_f32_16x16x32_bf16 v[20:23], v[224:227], v[204:207], v[20:23]
	s_waitcnt lgkmcnt(4)
	v_mfma_f32_16x16x32_bf16 v[42:45], v[228:231], v[188:191], v[42:45]
	v_mfma_f32_16x16x32_bf16 v[24:27], v[228:231], v[204:207], v[24:27]
	s_waitcnt lgkmcnt(2)
	v_mfma_f32_16x16x32_bf16 v[56:59], v[232:235], v[188:191], v[56:59]
	v_mfma_f32_16x16x32_bf16 v[38:41], v[232:235], v[204:207], v[38:41]
	s_waitcnt lgkmcnt(0)
	v_mfma_f32_16x16x32_bf16 v[60:63], v[216:219], v[188:191], v[60:63]
	v_mfma_f32_16x16x32_bf16 v[28:31], v[216:219], v[204:207], v[28:31]
	s_mov_b32 s42, s43
	s_mov_b32 s43, s51
	s_add_i32 s51, s51, 10240
	s_cmp_lg_u32 s51, 30720
	s_cselect_b32 s51, s51, 0
	s_min_u32 s8, s20, 60
	s_add_i32 s8, s8, 3
	s_mul_i32 s30, s8, 0xf8000
	s_nop 1
	s_waitcnt vmcnt(2)
	ds_write_b128 v120, v[208:211] offset:0
	ds_write_b128 v74, v[212:215] offset:20480
	s_mov_b32 s66, 0xff800000
	s_mov_b32 s67, 0xff800000
	s_cmp_ge_u32 s20, 1
	s_cselect_b32 s66, 0x5f800000, s66
	s_cselect_b32 s67, 0x42000000, s67
	s_add_i32 s20, s20, 1
	v_add_u32_e32 v72, s42, v119
	v_add_u32_e32 v74, s51, v120
	s_add_u32 s96, s80, s30
	s_addc_u32 s97, s81, 0
	s_add_u32 s98, s86, s30
	s_addc_u32 s99, s87, 0
	s_waitcnt lgkmcnt(0)
	s_barrier
	s_cmp_lt_u32 s20, 64
	s_cbranch_scc1 .Lb_loopB
	v_add_u32_e32 v72, s42, v119
	ds_read_b64_tr_b16 v[216:217], v72 offset:20480
	ds_read_b64_tr_b16 v[218:219], v72 offset:23040
	ds_read_b64_tr_b16 v[220:221], v72 offset:20512
	ds_read_b64_tr_b16 v[222:223], v72 offset:23072
	ds_read_b64_tr_b16 v[224:225], v72 offset:20544
	ds_read_b64_tr_b16 v[226:227], v72 offset:23104
	ds_read_b64_tr_b16 v[228:229], v72 offset:20576
	ds_read_b64_tr_b16 v[230:231], v72 offset:23136
	v_exp_f32_e32 v236, v88
	v_exp_f32_e32 v237, v89
	v_exp_f32_e32 v238, v90
	v_exp_f32_e32 v239, v91
	v_exp_f32_e32 v240, v92
	v_exp_f32_e32 v241, v93
	v_exp_f32_e32 v242, v94
	v_exp_f32_e32 v243, v95
	v_exp_f32_e32 v244, v96
	v_exp_f32_e32 v245, v97
	v_exp_f32_e32 v246, v98
	v_exp_f32_e32 v247, v99
	v_exp_f32_e32 v248, v100
	v_exp_f32_e32 v249, v101
	v_exp_f32_e32 v250, v102
	v_exp_f32_e32 v251, v103
	s_nop 0
	v_add_f32_e32 v67, v236, v237
	v_add_f32_e32 v67, v67, v238
	v_add_f32_e32 v67, v67, v239
	v_add_f32_e32 v67, v67, v240
	v_add_f32_e32 v67, v67, v241
	v_add_f32_e32 v67, v67, v242
	v_add_f32_e32 v67, v67, v243
	v_add_f32_e32 v67, v67, v244
	v_add_f32_e32 v67, v67, v245
	v_add_f32_e32 v67, v67, v246
	v_add_f32_e32 v67, v67, v247
	v_add_f32_e32 v67, v67, v248
	v_add_f32_e32 v67, v67, v249
	v_add_f32_e32 v67, v67, v250
	v_add_f32_e32 v67, v67, v251
	v_cmp_lt_f32_e32 vcc, s66, v67
	s_cbranch_vccnz .Lb_rare_Bt_0

.Lb_back_Bt_1:
	v_add_f32_e32 v64, v64, v67
	v_cvt_pk_bf16_f32 v184, v236, v237
	v_cvt_pk_bf16_f32 v185, v238, v239
	v_cvt_pk_bf16_f32 v186, v240, v241
	v_cvt_pk_bf16_f32 v187, v242, v243
	v_cvt_pk_bf16_f32 v204, v244, v245
	v_cvt_pk_bf16_f32 v205, v246, v247
	v_cvt_pk_bf16_f32 v206, v248, v249
	v_cvt_pk_bf16_f32 v207, v250, v251
	ds_read_b64_tr_b16 v[232:233], v72 offset:25600
	ds_read_b64_tr_b16 v[234:235], v72 offset:28160
	s_waitcnt lgkmcnt(8)
	v_mfma_f32_16x16x32_bf16 v[34:37], v[216:219], v[180:183], v[34:37]
	v_mfma_f32_16x16x32_bf16 v[20:23], v[216:219], v[184:187], v[20:23]
	ds_read_b64_tr_b16 v[216:217], v72 offset:25632
	ds_read_b64_tr_b16 v[218:219], v72 offset:28192
	s_waitcnt lgkmcnt(8)
	v_mfma_f32_16x16x32_bf16 v[42:45], v[220:223], v[180:183], v[42:45]
	v_mfma_f32_16x16x32_bf16 v[24:27], v[220:223], v[184:187], v[24:27]
	ds_read_b64_tr_b16 v[220:221], v72 offset:25664
	ds_read_b64_tr_b16 v[222:223], v72 offset:28224
	s_waitcnt lgkmcnt(8)
	v_mfma_f32_16x16x32_bf16 v[56:59], v[224:227], v[180:183], v[56:59]
	v_mfma_f32_16x16x32_bf16 v[38:41], v[224:227], v[184:187], v[38:41]
	ds_read_b64_tr_b16 v[224:225], v72 offset:25696
	ds_read_b64_tr_b16 v[226:227], v72 offset:28256
	s_waitcnt lgkmcnt(8)
	v_mfma_f32_16x16x32_bf16 v[60:63], v[228:231], v[180:183], v[60:63]
	v_mfma_f32_16x16x32_bf16 v[28:31], v[228:231], v[184:187], v[28:31]
	s_waitcnt lgkmcnt(6)
	v_mfma_f32_16x16x32_bf16 v[34:37], v[232:235], v[188:191], v[34:37]
	v_mfma_f32_16x16x32_bf16 v[20:23], v[232:235], v[204:207], v[20:23]
	s_waitcnt lgkmcnt(4)
	v_mfma_f32_16x16x32_bf16 v[42:45], v[216:219], v[188:191], v[42:45]
	v_mfma_f32_16x16x32_bf16 v[24:27], v[216:219], v[204:207], v[24:27]
	s_waitcnt lgkmcnt(2)
	v_mfma_f32_16x16x32_bf16 v[56:59], v[220:223], v[188:191], v[56:59]
	v_mfma_f32_16x16x32_bf16 v[38:41], v[220:223], v[204:207], v[38:41]
	s_waitcnt lgkmcnt(0)
	v_mfma_f32_16x16x32_bf16 v[60:63], v[224:227], v[188:191], v[60:63]
	v_mfma_f32_16x16x32_bf16 v[28:31], v[224:227], v[204:207], v[28:31]
	s_waitcnt vmcnt(0)
	v_mov_b32_e32 v138, 0xa00
	v_mov_b32_e32 v139, 0x0
	v_mov_b32_e32 v140, 0x9ff
	v_mov_b32_e32 v141, 0x0
	v_mov_b32_e32 v142, 0x200
	v_mov_b32_e32 v143, 0x0
	v_mov_b32_e32 v144, 0x1ff
	v_mov_b32_e32 v145, 0x0
	s_branch .LBB0_666

.Lb_groupA:
	s_waitcnt vmcnt(0)
	v_mov_b32_e32 v34, 0
	v_mov_b32_e32 v35, 0
	v_mov_b32_e32 v36, 0
	v_mov_b32_e32 v37, 0
	v_mov_b32_e32 v42, 0
	v_mov_b32_e32 v43, 0
	v_mov_b32_e32 v44, 0
	v_mov_b32_e32 v45, 0
	v_mov_b32_e32 v56, 0
	v_mov_b32_e32 v57, 0
	v_mov_b32_e32 v58, 0
	v_mov_b32_e32 v59, 0
	v_mov_b32_e32 v60, 0
	v_mov_b32_e32 v61, 0
	v_mov_b32_e32 v62, 0
	v_mov_b32_e32 v63, 0
	v_mov_b32_e32 v20, 0
	v_mov_b32_e32 v21, 0
	v_mov_b32_e32 v22, 0
	v_mov_b32_e32 v23, 0
	v_mov_b32_e32 v24, 0
	v_mov_b32_e32 v25, 0
	v_mov_b32_e32 v26, 0
	v_mov_b32_e32 v27, 0
	v_mov_b32_e32 v38, 0
	v_mov_b32_e32 v39, 0
	v_mov_b32_e32 v40, 0
	v_mov_b32_e32 v41, 0
	v_mov_b32_e32 v28, 0
	v_mov_b32_e32 v29, 0
	v_mov_b32_e32 v30, 0
	v_mov_b32_e32 v31, 0
	v_mov_b32_e32 v180, 0
	v_mov_b32_e32 v181, 0
	v_mov_b32_e32 v182, 0
	v_mov_b32_e32 v183, 0
	v_mov_b32_e32 v184, 0
	v_mov_b32_e32 v185, 0
	v_mov_b32_e32 v186, 0
	v_mov_b32_e32 v187, 0
	v_mov_b32_e32 v188, 0
	v_mov_b32_e32 v189, 0
	v_mov_b32_e32 v190, 0
	v_mov_b32_e32 v191, 0
	v_mov_b32_e32 v204, 0
	v_mov_b32_e32 v205, 0
	v_mov_b32_e32 v206, 0
	v_mov_b32_e32 v207, 0
	v_mov_b32_e32 v48, 0
	v_mov_b32_e32 v49, 0
	v_mov_b32_e32 v50, 0
	v_mov_b32_e32 v51, 0
	v_mov_b32_e32 v52, 0
	v_mov_b32_e32 v53, 0
	v_mov_b32_e32 v54, 0
	v_mov_b32_e32 v55, 0
	v_mov_b32_e32 v80, 0
	v_mov_b32_e32 v64, 0
	v_add_u32_e32 v75, v116, v0
	v_readfirstlane_b32 s80, v112
	v_readfirstlane_b32 s81, v113
	v_readfirstlane_b32 s86, v114
	v_readfirstlane_b32 s87, v115
	s_nop 3
	v_subrev_u32_e32 v71, s80, v112
	v_subrev_u32_e32 v73, s86, v114
	s_mov_b32 s20, 0
	s_mov_b32 s42, 0
	s_mov_b32 s43, 0
	s_mov_b32 s51, 10240
	s_mov_b32 s30, 0xf8000
	s_mov_b32 s66, 0xff800000
	s_mov_b32 s67, 0xff800000
	v_add_u32_e32 v72, s42, v119
	v_add_u32_e32 v74, s51, v120
	s_add_u32 s96, s80, s30
	s_addc_u32 s97, s81, 0
	s_add_u32 s98, s86, s30
	s_addc_u32 s99, s87, 0
	global_load_dwordx4 v[138:141], v71, s[96:97]
	global_load_dwordx4 v[142:145], v73, s[98:99]
	s_mov_b32 s30, 0x1f0000
	v_add_u32_e32 v72, s42, v119
	v_add_u32_e32 v74, s51, v120
	s_add_u32 s96, s80, s30
	s_addc_u32 s97, s81, 0
	s_add_u32 s98, s86, s30
	s_addc_u32 s99, s87, 0
.Lb_loopA:
	global_load_dwordx4 v[208:211], v71, s[96:97]
	global_load_dwordx4 v[212:215], v73, s[98:99]
	ds_read_b64_tr_b16 v[216:217], v72 offset:20480
	ds_read_b64_tr_b16 v[218:219], v72 offset:23040
	ds_read_b64_tr_b16 v[220:221], v72 offset:20512
	ds_read_b64_tr_b16 v[222:223], v72 offset:23072
	ds_read_b64_tr_b16 v[224:225], v72 offset:20544
	ds_read_b64_tr_b16 v[226:227], v72 offset:23104
	ds_read_b64_tr_b16 v[228:229], v72 offset:20576
	ds_read_b64_tr_b16 v[230:231], v72 offset:23136
	ds_read_b64_tr_b16 v[232:233], v72 offset:25600
	ds_read_b64_tr_b16 v[234:235], v72 offset:28160
	s_waitcnt lgkmcnt(8)
	v_mfma_f32_16x16x32_bf16 v[34:37], v[216:219], v[180:183], v[34:37]
	v_mfma_f32_16x16x32_bf16 v[20:23], v[216:219], v[184:187], v[20:23]
	ds_read_b64_tr_b16 v[216:217], v72 offset:25632
	ds_read_b64_tr_b16 v[218:219], v72 offset:28192
	s_waitcnt lgkmcnt(8)
	v_mfma_f32_16x16x32_bf16 v[42:45], v[220:223], v[180:183], v[42:45]
	v_mfma_f32_16x16x32_bf16 v[24:27], v[220:223], v[184:187], v[24:27]
	ds_read_b64_tr_b16 v[220:221], v72 offset:25664
	ds_read_b64_tr_b16 v[222:223], v72 offset:28224
	s_waitcnt lgkmcnt(8)
	v_mfma_f32_16x16x32_bf16 v[56:59], v[224:227], v[180:183], v[56:59]
	v_mfma_f32_16x16x32_bf16 v[38:41], v[224:227], v[184:187], v[38:41]
	ds_read_b64_tr_b16 v[224:225], v72 offset:25696
	ds_read_b64_tr_b16 v[226:227], v72 offset:28256
	s_waitcnt lgkmcnt(8)
	v_mfma_f32_16x16x32_bf16 v[60:63], v[228:231], v[180:183], v[60:63]
	v_mfma_f32_16x16x32_bf16 v[28:31], v[228:231], v[184:187], v[28:31]
	ds_read_b128 v[228:231], v75 offset:0
	s_waitcnt lgkmcnt(7)
	v_mfma_f32_16x16x32_bf16 v[34:37], v[232:235], v[188:191], v[34:37]
	v_mfma_f32_16x16x32_bf16 v[20:23], v[232:235], v[204:207], v[20:23]
	ds_read_b128 v[232:235], v75 offset:64
	s_waitcnt lgkmcnt(6)
	v_mfma_f32_16x16x32_bf16 v[42:45], v[216:219], v[188:191], v[42:45]
	v_mfma_f32_16x16x32_bf16 v[24:27], v[216:219], v[204:207], v[24:27]
	ds_read_b128 v[216:219], v75 offset:2560
	s_waitcnt lgkmcnt(5)
	v_mfma_f32_16x16x32_bf16 v[56:59], v[220:223], v[188:191], v[56:59]
	v_mfma_f32_16x16x32_bf16 v[38:41], v[220:223], v[204:207], v[38:41]
	ds_read_b128 v[220:223], v75 offset:2624
	s_waitcnt lgkmcnt(4)
	v_mfma_f32_16x16x32_bf16 v[60:63], v[224:227], v[188:191], v[60:63]
	v_mfma_f32_16x16x32_bf16 v[28:31], v[224:227], v[204:207], v[28:31]
	ds_read_b128 v[224:227], v75 offset:5120
	s_waitcnt lgkmcnt(4)
	v_mfma_f32_16x16x32_bf16 v[88:91], v[228:231], v[16:19], v[48:51]
	v_mfma_f32_16x16x32_bf16 v[104:107], v[228:231], v[12:15], v[52:55]
	ds_read_b128 v[228:231], v75 offset:5184
	s_waitcnt lgkmcnt(4)
	v_mfma_f32_16x16x32_bf16 v[88:91], v[232:235], v[8:11], v[88:91]
	v_mfma_f32_16x16x32_bf16 v[104:107], v[232:235], v[4:7], v[104:107]
	ds_read_b128 v[232:235], v75 offset:7680
	s_waitcnt lgkmcnt(4)
	v_mfma_f32_16x16x32_bf16 v[92:95], v[216:219], v[16:19], v[48:51]
	v_mfma_f32_16x16x32_bf16 v[168:171], v[216:219], v[12:15], v[52:55]
	ds_read_b128 v[216:219], v75 offset:7744
	s_waitcnt lgkmcnt(4)
	v_mfma_f32_16x16x32_bf16 v[92:95], v[220:223], v[8:11], v[92:95]
	v_mfma_f32_16x16x32_bf16 v[168:171], v[220:223], v[4:7], v[168:171]
	s_waitcnt lgkmcnt(3)
	v_mfma_f32_16x16x32_bf16 v[96:99], v[224:227], v[16:19], v[48:51]
	v_mfma_f32_16x16x32_bf16 v[172:175], v[224:227], v[12:15], v[52:55]
	s_waitcnt lgkmcnt(2)
	v_mfma_f32_16x16x32_bf16 v[96:99], v[228:231], v[8:11], v[96:99]
	v_mfma_f32_16x16x32_bf16 v[172:175], v[228:231], v[4:7], v[172:175]
	s_waitcnt lgkmcnt(1)
	v_mfma_f32_16x16x32_bf16 v[100:103], v[232:235], v[16:19], v[48:51]
	v_mfma_f32_16x16x32_bf16 v[176:179], v[232:235], v[12:15], v[52:55]
	s_waitcnt lgkmcnt(0)
	v_mfma_f32_16x16x32_bf16 v[100:103], v[216:219], v[8:11], v[100:103]
	v_mfma_f32_16x16x32_bf16 v[176:179], v[216:219], v[4:7], v[176:179]
	s_mov_b32 s42, s43
	s_mov_b32 s43, s51
	s_add_i32 s51, s51, 10240
	s_cmp_lg_u32 s51, 30720
	s_cselect_b32 s51, s51, 0
	s_min_u32 s8, s20, 60
	s_add_i32 s8, s8, 3
	s_mul_i32 s30, s8, 0xf8000
	s_nop 1
	v_exp_f32_e32 v236, v88
	v_exp_f32_e32 v237, v89
	v_exp_f32_e32 v238, v90
	v_exp_f32_e32 v239, v91
	v_exp_f32_e32 v240, v92
	v_exp_f32_e32 v241, v93
	v_exp_f32_e32 v242, v94
	v_exp_f32_e32 v243, v95
	v_exp_f32_e32 v244, v96
	v_exp_f32_e32 v245, v97
	v_exp_f32_e32 v246, v98
	v_exp_f32_e32 v247, v99
	v_exp_f32_e32 v248, v100
	v_exp_f32_e32 v249, v101
	v_exp_f32_e32 v250, v102
	v_exp_f32_e32 v251, v103
	s_nop 0
	v_add_f32_e32 v67, v236, v237
	v_add_f32_e32 v67, v67, v238
	v_add_f32_e32 v67, v67, v239
	v_add_f32_e32 v67, v67, v240
	v_add_f32_e32 v67, v67, v241
	v_add_f32_e32 v67, v67, v242
	v_add_f32_e32 v67, v67, v243
	v_add_f32_e32 v67, v67, v244
	v_add_f32_e32 v67, v67, v245
	v_add_f32_e32 v67, v67, v246
	v_add_f32_e32 v67, v67, v247
	v_add_f32_e32 v67, v67, v248
	v_add_f32_e32 v67, v67, v249
	v_add_f32_e32 v67, v67, v250
	v_add_f32_e32 v67, v67, v251
	v_cmp_lt_f32_e32 vcc, s66, v67
	s_cbranch_vccnz .Lb_rare_A0_0

.Lb_back_A0_1:
	v_add_f32_e32 v64, v64, v67
	v_cvt_pk_bf16_f32 v184, v236, v237
	v_cvt_pk_bf16_f32 v185, v238, v239
	v_cvt_pk_bf16_f32 v186, v240, v241
	v_cvt_pk_bf16_f32 v187, v242, v243
	v_cvt_pk_bf16_f32 v204, v244, v245
	v_cvt_pk_bf16_f32 v205, v246, v247
	v_cvt_pk_bf16_f32 v206, v248, v249
	v_cvt_pk_bf16_f32 v207, v250, v251
	s_waitcnt vmcnt(2)
	ds_write_b128 v120, v[138:141] offset:10240
	ds_write_b128 v74, v[142:145] offset:20480
	s_mov_b32 s66, 0x5f800000
	s_mov_b32 s67, 0x42000000
	s_add_i32 s20, s20, 1
	v_add_u32_e32 v72, s42, v119
	v_add_u32_e32 v74, s51, v120
	s_add_u32 s96, s80, s30
	s_addc_u32 s97, s81, 0
	s_add_u32 s98, s86, s30
	s_addc_u32 s99, s87, 0
	s_waitcnt lgkmcnt(0)
	s_barrier
	global_load_dwordx4 v[138:141], v71, s[96:97]
	global_load_dwordx4 v[142:145], v73, s[98:99]
	ds_read_b64_tr_b16 v[216:217], v72 offset:20480
	ds_read_b64_tr_b16 v[218:219], v72 offset:23040
	ds_read_b64_tr_b16 v[220:221], v72 offset:20512
	ds_read_b64_tr_b16 v[222:223], v72 offset:23072
	ds_read_b64_tr_b16 v[224:225], v72 offset:20544
	ds_read_b64_tr_b16 v[226:227], v72 offset:23104
	ds_read_b64_tr_b16 v[228:229], v72 offset:20576
	ds_read_b64_tr_b16 v[230:231], v72 offset:23136
	ds_read_b64_tr_b16 v[232:233], v72 offset:25600
	ds_read_b64_tr_b16 v[234:235], v72 offset:28160
	s_waitcnt lgkmcnt(8)
	v_mfma_f32_16x16x32_bf16 v[34:37], v[216:219], v[180:183], v[34:37]
	v_mfma_f32_16x16x32_bf16 v[20:23], v[216:219], v[184:187], v[20:23]
	ds_read_b64_tr_b16 v[216:217], v72 offset:25632
	ds_read_b64_tr_b16 v[218:219], v72 offset:28192
	s_waitcnt lgkmcnt(8)
	v_mfma_f32_16x16x32_bf16 v[42:45], v[220:223], v[180:183], v[42:45]
	v_mfma_f32_16x16x32_bf16 v[24:27], v[220:223], v[184:187], v[24:27]
	ds_read_b64_tr_b16 v[220:221], v72 offset:25664
	ds_read_b64_tr_b16 v[222:223], v72 offset:28224
	s_waitcnt lgkmcnt(8)
	v_mfma_f32_16x16x32_bf16 v[56:59], v[224:227], v[180:183], v[56:59]
	v_mfma_f32_16x16x32_bf16 v[38:41], v[224:227], v[184:187], v[38:41]
	ds_read_b64_tr_b16 v[224:225], v72 offset:25696
	ds_read_b64_tr_b16 v[226:227], v72 offset:28256
	s_waitcnt lgkmcnt(8)
	v_mfma_f32_16x16x32_bf16 v[60:63], v[228:231], v[180:183], v[60:63]
	v_mfma_f32_16x16x32_bf16 v[28:31], v[228:231], v[184:187], v[28:31]
	ds_read_b128 v[228:231], v75 offset:10240
	s_waitcnt lgkmcnt(7)
	v_mfma_f32_16x16x32_bf16 v[34:37], v[232:235], v[188:191], v[34:37]
	v_mfma_f32_16x16x32_bf16 v[20:23], v[232:235], v[204:207], v[20:23]
	ds_read_b128 v[232:235], v75 offset:10304
	s_waitcnt lgkmcnt(6)
	v_mfma_f32_16x16x32_bf16 v[42:45], v[216:219], v[188:191], v[42:45]
	v_mfma_f32_16x16x32_bf16 v[24:27], v[216:219], v[204:207], v[24:27]
	ds_read_b128 v[216:219], v75 offset:12800
	s_waitcnt lgkmcnt(5)
	v_mfma_f32_16x16x32_bf16 v[56:59], v[220:223], v[188:191], v[56:59]
	v_mfma_f32_16x16x32_bf16 v[38:41], v[220:223], v[204:207], v[38:41]
	ds_read_b128 v[220:223], v75 offset:12864
	s_waitcnt lgkmcnt(4)
	v_mfma_f32_16x16x32_bf16 v[60:63], v[224:227], v[188:191], v[60:63]
	v_mfma_f32_16x16x32_bf16 v[28:31], v[224:227], v[204:207], v[28:31]
	ds_read_b128 v[224:227], v75 offset:15360
	s_waitcnt lgkmcnt(4)
	v_mfma_f32_16x16x32_bf16 v[88:91], v[228:231], v[16:19], v[48:51]
	v_mfma_f32_16x16x32_bf16 v[104:107], v[228:231], v[12:15], v[52:55]
	ds_read_b128 v[228:231], v75 offset:15424
	s_waitcnt lgkmcnt(4)
	v_mfma_f32_16x16x32_bf16 v[88:91], v[232:235], v[8:11], v[88:91]
	v_mfma_f32_16x16x32_bf16 v[104:107], v[232:235], v[4:7], v[104:107]
	ds_read_b128 v[232:235], v75 offset:17920
	s_waitcnt lgkmcnt(4)
	v_mfma_f32_16x16x32_bf16 v[92:95], v[216:219], v[16:19], v[48:51]
	v_mfma_f32_16x16x32_bf16 v[168:171], v[216:219], v[12:15], v[52:55]
	ds_read_b128 v[216:219], v75 offset:17984
	s_waitcnt lgkmcnt(4)
	v_mfma_f32_16x16x32_bf16 v[92:95], v[220:223], v[8:11], v[92:95]
	v_mfma_f32_16x16x32_bf16 v[168:171], v[220:223], v[4:7], v[168:171]
	s_waitcnt lgkmcnt(3)
	v_mfma_f32_16x16x32_bf16 v[96:99], v[224:227], v[16:19], v[48:51]
	v_mfma_f32_16x16x32_bf16 v[172:175], v[224:227], v[12:15], v[52:55]
	s_waitcnt lgkmcnt(2)
	v_mfma_f32_16x16x32_bf16 v[96:99], v[228:231], v[8:11], v[96:99]
	v_mfma_f32_16x16x32_bf16 v[172:175], v[228:231], v[4:7], v[172:175]
	s_waitcnt lgkmcnt(1)
	v_mfma_f32_16x16x32_bf16 v[100:103], v[232:235], v[16:19], v[48:51]
	v_mfma_f32_16x16x32_bf16 v[176:179], v[232:235], v[12:15], v[52:55]
	s_waitcnt lgkmcnt(0)
	v_mfma_f32_16x16x32_bf16 v[100:103], v[216:219], v[8:11], v[100:103]
	v_mfma_f32_16x16x32_bf16 v[176:179], v[216:219], v[4:7], v[176:179]
	s_mov_b32 s42, s43
	s_mov_b32 s43, s51
	s_add_i32 s51, s51, 10240
	s_cmp_lg_u32 s51, 30720
	s_cselect_b32 s51, s51, 0
	s_min_u32 s8, s20, 60
	s_add_i32 s8, s8, 3
	s_mul_i32 s30, s8, 0xf8000
	s_nop 1
	v_exp_f32_e32 v236, v88
	v_exp_f32_e32 v237, v89
	v_exp_f32_e32 v238, v90
	v_exp_f32_e32 v239, v91
	v_exp_f32_e32 v240, v92
	v_exp_f32_e32 v241, v93
	v_exp_f32_e32 v242, v94
	v_exp_f32_e32 v243, v95
	v_exp_f32_e32 v244, v96
	v_exp_f32_e32 v245, v97
	v_exp_f32_e32 v246, v98
	v_exp_f32_e32 v247, v99
	v_exp_f32_e32 v248, v100
	v_exp_f32_e32 v249, v101
	v_exp_f32_e32 v250, v102
	v_exp_f32_e32 v251, v103
	s_nop 0
	v_add_f32_e32 v67, v236, v237
	v_add_f32_e32 v67, v67, v238
	v_add_f32_e32 v67, v67, v239
	v_add_f32_e32 v67, v67, v240
	v_add_f32_e32 v67, v67, v241
	v_add_f32_e32 v67, v67, v242
	v_add_f32_e32 v67, v67, v243
	v_add_f32_e32 v67, v67, v244
	v_add_f32_e32 v67, v67, v245
	v_add_f32_e32 v67, v67, v246
	v_add_f32_e32 v67, v67, v247
	v_add_f32_e32 v67, v67, v248
	v_add_f32_e32 v67, v67, v249
	v_add_f32_e32 v67, v67, v250
	v_add_f32_e32 v67, v67, v251
	v_cmp_lt_f32_e32 vcc, s66, v67
	s_cbranch_vccnz .Lb_rare_A1_0

.Lb_back_A1_1:
	v_add_f32_e32 v64, v64, v67
	v_cvt_pk_bf16_f32 v184, v236, v237
	v_cvt_pk_bf16_f32 v185, v238, v239
	v_cvt_pk_bf16_f32 v186, v240, v241
	v_cvt_pk_bf16_f32 v187, v242, v243
	v_cvt_pk_bf16_f32 v204, v244, v245
	v_cvt_pk_bf16_f32 v205, v246, v247
	v_cvt_pk_bf16_f32 v206, v248, v249
	v_cvt_pk_bf16_f32 v207, v250, v251
	s_waitcnt vmcnt(2)
	ds_write_b128 v120, v[208:211] offset:0
	ds_write_b128 v74, v[212:215] offset:20480
	s_mov_b32 s66, 0x5f800000
	s_mov_b32 s67, 0x42000000
	s_add_i32 s20, s20, 1
	v_add_u32_e32 v72, s42, v119
	v_add_u32_e32 v74, s51, v120
	s_add_u32 s96, s80, s30
	s_addc_u32 s97, s81, 0
	s_add_u32 s98, s86, s30
	s_addc_u32 s99, s87, 0
	s_waitcnt lgkmcnt(0)
	s_barrier
	s_cmp_lt_u32 s20, 64
	s_cbranch_scc1 .Lb_loopA
	v_add_u32_e32 v72, s42, v119
	ds_read_b64_tr_b16 v[216:217], v72 offset:20480
	ds_read_b64_tr_b16 v[218:219], v72 offset:23040
	ds_read_b64_tr_b16 v[220:221], v72 offset:20512
	ds_read_b64_tr_b16 v[222:223], v72 offset:23072
	ds_read_b64_tr_b16 v[224:225], v72 offset:20544
	ds_read_b64_tr_b16 v[226:227], v72 offset:23104
	ds_read_b64_tr_b16 v[228:229], v72 offset:20576
	ds_read_b64_tr_b16 v[230:231], v72 offset:23136
	ds_read_b64_tr_b16 v[232:233], v72 offset:25600
	ds_read_b64_tr_b16 v[234:235], v72 offset:28160
	s_waitcnt lgkmcnt(8)
	v_mfma_f32_16x16x32_bf16 v[34:37], v[216:219], v[180:183], v[34:37]
	v_mfma_f32_16x16x32_bf16 v[20:23], v[216:219], v[184:187], v[20:23]
	ds_read_b64_tr_b16 v[216:217], v72 offset:25632
	ds_read_b64_tr_b16 v[218:219], v72 offset:28192
	s_waitcnt lgkmcnt(8)
	v_mfma_f32_16x16x32_bf16 v[42:45], v[220:223], v[180:183], v[42:45]
	v_mfma_f32_16x16x32_bf16 v[24:27], v[220:223], v[184:187], v[24:27]
	ds_read_b64_tr_b16 v[220:221], v72 offset:25664
	ds_read_b64_tr_b16 v[222:223], v72 offset:28224
	s_waitcnt lgkmcnt(8)
	v_mfma_f32_16x16x32_bf16 v[56:59], v[224:227], v[180:183], v[56:59]
	v_mfma_f32_16x16x32_bf16 v[38:41], v[224:227], v[184:187], v[38:41]
	ds_read_b64_tr_b16 v[224:225], v72 offset:25696
	ds_read_b64_tr_b16 v[226:227], v72 offset:28256
	s_waitcnt lgkmcnt(8)
	v_mfma_f32_16x16x32_bf16 v[60:63], v[228:231], v[180:183], v[60:63]
	v_mfma_f32_16x16x32_bf16 v[28:31], v[228:231], v[184:187], v[28:31]
	s_waitcnt lgkmcnt(6)
	v_mfma_f32_16x16x32_bf16 v[34:37], v[232:235], v[188:191], v[34:37]
	v_mfma_f32_16x16x32_bf16 v[20:23], v[232:235], v[204:207], v[20:23]
	s_waitcnt lgkmcnt(4)
	v_mfma_f32_16x16x32_bf16 v[42:45], v[216:219], v[188:191], v[42:45]
	v_mfma_f32_16x16x32_bf16 v[24:27], v[216:219], v[204:207], v[24:27]
	s_waitcnt lgkmcnt(2)
	v_mfma_f32_16x16x32_bf16 v[56:59], v[220:223], v[188:191], v[56:59]
	v_mfma_f32_16x16x32_bf16 v[38:41], v[220:223], v[204:207], v[38:41]
	s_waitcnt lgkmcnt(0)
	v_mfma_f32_16x16x32_bf16 v[60:63], v[224:227], v[188:191], v[60:63]
	v_mfma_f32_16x16x32_bf16 v[28:31], v[224:227], v[204:207], v[28:31]
	s_waitcnt vmcnt(0)
	v_mov_b32_e32 v138, 0xa00
	v_mov_b32_e32 v139, 0x0
	v_mov_b32_e32 v140, 0x9ff
	v_mov_b32_e32 v141, 0x0
	v_mov_b32_e32 v142, 0x200
	v_mov_b32_e32 v143, 0x0
	v_mov_b32_e32 v144, 0x1ff
	v_mov_b32_e32 v145, 0x0
